# v48 + same store-drain removal for the in-proj and down GEMM tile starts
# speedup vs baseline: 1.0123x; 1.0032x over previous
; #define PG8_STAGE(bufoff, gbase, voff) do { _Pragma("unroll") for (int _i = 0; _i < 2; ++_i) \
;         __builtin_amdgcn_global_load_lds((const unsigned*)((const char*)(gbase) + (voff)[_i]), (PG8_LAS unsigned*)(lds + (bufoff) + ldsw + _i * 8192), 16, 0, 0); } while (0)
; #define PG8_WAIT_V(n) asm volatile("s_waitcnt vmcnt(" #n ")" ::: "memory")
; #define PG8_BAR __builtin_amdgcn_s_barrier()
; template <class Epi, class Sched, bool ALIGN_EPI = false, bool SP2 = false, bool F16 = false>
; __device__ __forceinline__ void gemm_phase(PG8_LAS unsigned char* lds, const Gemm g, const Sched& S, const Epi& E) {
;     ...
;     for (int i = 0; i < 2; ++i) { int R, C; stage_rc(tid * 16 + i * 8192, R, C); const int Rb = Epi::PERM ? ((R & ~31) + perm32(R & 31)) : R;
;         voffA[i] = (unsigned)(R * K + C) * 2u; voffB[i] = (unsigned)(Rb * K + C) * 2u; }
;     const size_t kstep = (size_t)(BK * 2);
;     const size_t hstep = (size_t)HALF * K * 2;
;     const size_t tstep = 2 * hstep;
;     const unsigned ldsw = (unsigned)wid * 1024u;
;     const int aoff = lds_byte(wr * 64 + fr, fq * 8), boff = lds_byte(wc * 32 + fr, fq * 8);
;     ...
;         PG8_STAGE(PG8_SB(0, 0), cB, voffB); PG8_STAGE(PG8_SB(0, 1), cB + hstep, voffB); PG8_STAGE(PG8_SA(0, 0), cA, voffA); PG8_STAGE(PG8_SA(0, 1), cA + hstep, voffA);
;         if (wr == 1) PG8_BAR;
;         PG8_WAIT_V(2); PG8_BAR;
;         PG8_STAGE(PG8_SB(1, 0), cB + kstep, voffB); PG8_STAGE(PG8_SA(1, 0), cA + kstep, voffA); PG8_STAGE(PG8_SB(1, 1), cB + hstep + kstep, voffB);
;         PG8_WAIT_V(6); PG8_BAR;
.LBB0_246:
	s_lshl_b32 s6, s60, 16
	s_mov_b32 s7, s35
	s_lshl_b32 s34, s60, 6
	s_lshl_b64 s[6:7], s[6:7], 2
	v_readlane_b32 s5, v252, 48
	s_add_u32 s12, s5, s6
	s_addc_u32 s13, s28, s7
	s_lshl_b64 s[6:7], s[60:61], 14
	v_readlane_b32 s5, v252, 57
	s_add_u32 s79, s5, s6
	v_readlane_b32 s5, v252, 58
	s_addc_u32 s10, s5, s7
	s_lshl_b64 s[6:7], s[60:61], 6
	v_readlane_b32 s46, v254, 43
	s_add_u32 s6, s76, s6
	v_mov_b32_e32 v149, v129
	v_readlane_b32 s47, v254, 44
	s_addc_u32 s7, s77, s7
	s_and_b32 s38, s1, 3
	s_add_i32 m0, s21, 0x18000
	v_lshl_add_u64 v[0:1], v[0:1], 0, s[16:17]
	v_lshl_add_u64 v[12:13], s[46:47], 0, v[148:149]
	v_mov_b32_e32 v145, v129
	s_lshl_b32 s11, s4, 6
	s_lshl_b32 s8, s4, 13
	s_lshl_b32 s28, s38, 5
	s_lshl_b32 s9, s38, 12
	s_waitcnt vmcnt(2)
	s_barrier
	global_load_lds_dwordx4 v[0:1], off
	v_lshl_add_u64 v[0:1], v[2:3], 0, s[16:17]
	s_add_i32 m0, s21, 0x1a000
	s_add_i32 s44, s21, 0x8000
	s_add_i32 s45, s21, 0xa000
	s_waitcnt lgkmcnt(0)
	v_lshl_add_u64 v[14:15], s[46:47], 0, v[144:145]
	global_load_lds_dwordx4 v[0:1], off
	v_lshl_add_u64 v[0:1], v[12:13], 0, s[16:17]
	s_mov_b32 m0, s44
	s_add_u32 s4, s42, 0x40080
	global_load_lds_dwordx4 v[0:1], off
	v_lshl_add_u64 v[0:1], v[14:15], 0, s[16:17]
	s_mov_b32 m0, s45
	s_addc_u32 s5, s43, 0
	global_load_lds_dwordx4 v[0:1], off
	s_add_i32 m0, s21, 0x1c000
	v_lshl_add_u64 v[0:1], s[4:5], 0, v[146:147]
	global_load_lds_dwordx4 v[0:1], off
	v_lshl_add_u64 v[0:1], s[4:5], 0, v[142:143]
	s_add_i32 m0, s21, 0x1e000
	v_and_b32_e32 v237, 15, v7
	global_load_lds_dwordx4 v[0:1], off
	v_bfe_u32 v238, v7, 4, 2
	v_lshlrev_b32_e32 v128, 6, v237
	v_lshlrev_b32_e32 v1, 2, v7
	v_lshl_or_b32 v0, v238, 4, v128
	v_and_b32_e32 v1, 32, v1
	s_cmpk_lt_u32 s0, 0x100
	v_bitop3_b32 v3, v0, s8, v1 bitop3:0xde
	v_bitop3_b32 v239, v0, s9, v1 bitop3:0xde
	s_cselect_b64 s[8:9], -1, 0
	s_lshl_b32 s81, s38, 6
	s_add_i32 s40, s81, 0xffffff80
	s_or_b32 s41, s81, 0x100
	s_and_b32 s1, s1, 2
	v_writelane_b32 v255, s1, 20
	s_cmp_lt_u32 s38, 2
	v_cmp_eq_u32_e64 s[4:5], 0, v237
	s_cselect_b64 s[38:39], -1, 0
	v_lshlrev_b32_e32 v1, 4, v237
	v_writelane_b32 v255, s4, 21
	v_or_b32_e32 v0, 0x100, v1
	v_or_b32_e32 v2, 0x200, v1
	v_or_b32_e32 v12, 0x300, v1
	v_writelane_b32 v255, s5, 22
	s_and_b64 s[4:5], s[38:39], exec
	v_lshlrev_b32_e32 v1, 14, v9
	s_cselect_b32 s1, s41, s40
	s_lshr_b32 s0, s0, 4
	v_and_b32_e32 v1, 0xffff8000, v1
	s_and_b32 s0, s0, 4
	v_lshl_add_u32 v1, v8, 11, v1
	v_and_b32_e32 v7, 1, v9
	s_add_u32 s0, s6, s0
	v_lshl_or_b32 v1, v7, 6, v1
	v_writelane_b32 v255, s1, 23
	s_addc_u32 s1, s7, 0
	v_lshl_add_u32 v154, v10, 1, v1
	v_lshlrev_b32_e32 v1, 14, v4
	v_writelane_b32 v255, s0, 24
	v_and_b32_e32 v1, 0xffff8000, v1
	s_waitcnt vmcnt(6)
	v_readlane_b32 s82, v252, 53
	v_writelane_b32 v255, s1, 25
	v_readlane_b32 s84, v252, 55
	v_lshl_add_u32 v1, v5, 11, v1
	v_and_b32_e32 v4, 1, v4
	v_readlane_b32 s0, v254, 40
	v_readlane_b32 s83, v252, 54
	v_readlane_b32 s85, v252, 56
	v_lshl_or_b32 v1, v4, 6, v1
	v_readlane_b32 s1, v254, 41
	s_mov_b32 s78, 0
	v_lshl_add_u64 v[150:151], s[82:83], 0, v[128:129]
	v_lshl_add_u64 v[152:153], s[84:85], 0, v[128:129]
	v_mov_b32_e32 v155, v129
	v_lshl_add_u32 v156, v6, 1, v1
	v_mov_b32_e32 v157, v129
	v_add_u32_e32 v240, 0, v3
	s_mov_b32 s91, s28
	s_lshl_b32 s80, s28, 2
	s_lshl_b64 s[76:77], s[34:35], 2
	v_lshlrev_b32_e32 v128, 2, v0
	v_lshlrev_b32_e32 v158, 2, v2
	v_lshlrev_b32_e32 v160, 2, v12
	v_readlane_b32 s66, v254, 36
	s_mov_b32 s6, s0
	s_mov_b64 s[0:1], s[46:47]
	s_waitcnt vmcnt(0)
	s_barrier
	v_readlane_b32 s67, v254, 37
	s_branch .LBB0_249

; #define PG8_STAGE(bufoff, gbase, voff) do { _Pragma("unroll") for (int _i = 0; _i < 2; ++_i) \
;         __builtin_amdgcn_global_load_lds((const unsigned*)((const char*)(gbase) + (voff)[_i]), (PG8_LAS unsigned*)(lds + (bufoff) + ldsw + _i * 8192), 16, 0, 0); } while (0)
; #define PG8_LDA(dst, b, h) do { _Pragma("unroll") for (int m = 0; m < 4; ++m) _Pragma("unroll") for (int k = 0; k < 2; ++k) dst[m][k] = *(const PG8_LAS bf16x8*)(lds + PG8_SA(b, h) + aoff + m * 2048 + k * 1024); } while (0)
; #define PG8_LDB(dst, b, h) do { _Pragma("unroll") for (int n = 0; n < 2; ++n) _Pragma("unroll") for (int k = 0; k < 2; ++k) dst[n][k] = *(const PG8_LAS bf16x8*)(lds + PG8_SB(b, h) + boff + n * 2048 + k * 1024); } while (0)
; #define PG8_MMA(ai, bj, At, Bt) do { __builtin_amdgcn_s_setprio(1); _Pragma("unroll") for (int m = 0; m < 4; ++m) _Pragma("unroll") for (int n = 0; n < 2; ++n) _Pragma("unroll") for (int k = 0; k < 2; ++k) \
;         acc[ai][bj][m][n] = mma16<F16>(Bt[n][k], At[m][k], acc[ai][bj][m][n]); __builtin_amdgcn_s_setprio(0); } while (0)
; #define PG8_WAIT_V(n) asm volatile("s_waitcnt vmcnt(" #n ")" ::: "memory")
; #define PG8_WAIT_L(n) asm volatile("s_waitcnt lgkmcnt(" #n ")" ::: "memory")
; #define PG8_BAR __builtin_amdgcn_s_barrier()
; #define PG8_SCHED __builtin_amdgcn_sched_barrier(0)
; template <class Epi, class Sched, bool ALIGN_EPI = false, bool SP2 = false, bool F16 = false>
; __device__ __forceinline__ void gemm_phase(PG8_LAS unsigned char* lds, const Gemm g, const Sched& S, const Epi& E) {
;     ...
;             PG8_LDB(B0, 0, 0); PG8_LDB(B1, 0, 1); PG8_SCHED; PG8_LDA(At, 0, 0); PG8_STAGE(PG8_SA(1, 1), a1 + hstep, voffA);
;             PG8_WAIT_V(8); PG8_WAIT_L(0); PG8_BAR; PG8_MMA(0, 0, At, B0); PG8_MMA(0, 1, At, B1); PG8_BAR; PG8_SCHED;
;             PG8_LDA(At, 0, 1); PG8_STAGE(PG8_SB(0, 0), b2, voffB); PG8_STAGE(PG8_SB(0, 1), b2 + hstep, voffB); PG8_STAGE(PG8_SA(0, 0), a2, voffA);
;             PG8_WAIT_V(8); PG8_WAIT_L(0); PG8_BAR; PG8_MMA(1, 0, At, B0); PG8_MMA(1, 1, At, B1); PG8_BAR; PG8_SCHED;
.LBB0_255:
	s_ashr_i32 s29, s28, 31
	s_lshl_b64 s[4:5], s[28:29], 19
	s_add_u32 s46, s96, s4
	s_addc_u32 s47, s97, s5
	s_and_b64 s[4:5], s[40:41], exec
	s_cselect_b32 s4, s47, s1
	s_cselect_b32 s5, s46, s0
	s_ashr_i32 s73, s72, 31
	s_lshl_b64 s[54:55], s[72:73], 19
	s_add_u32 s7, s30, s54
	s_addc_u32 s34, s31, s55
	s_cmp_gt_i32 s28, 63
	s_cselect_b32 s54, 0x400000, 0
	s_add_u32 s64, s7, s54
	s_addc_u32 s65, s34, 0
	s_and_b64 s[54:55], s[40:41], exec
	s_cselect_b32 s7, s65, s43
	s_cselect_b32 s34, s64, s42
	s_add_u32 s0, s0, 0x40080
	s_addc_u32 s1, s1, 0
	s_add_u32 s59, s42, 0x100
	s_addc_u32 s61, s43, 0
	s_mov_b32 s67, -2
	v_add_u32_e32 v242, 0x10000, v239
	s_add_u32 s42, s0, 0xfffc0080
	s_addc_u32 s43, s1, -1
	s_add_i32 s68, 0, 0x10000
	s_cmp_eq_u32 s67, 12
	s_cselect_b32 s55, s4, s43
	s_cselect_b32 s54, s5, s42
	s_cselect_b32 s43, s7, s61
	s_cselect_b32 s42, s34, s59
	s_add_i32 s70, 0, 0x14000
	ds_read_b128 v[130:133], v242
	ds_read_b128 v[134:137], v242 offset:1024
	ds_read_b128 v[138:141], v242 offset:2048
	ds_read_b128 v[162:165], v242 offset:3072
	ds_read_b128 v[166:169], v242 offset:16384
	ds_read_b128 v[170:173], v242 offset:17408
	ds_read_b128 v[186:189], v242 offset:18432
	ds_read_b128 v[190:193], v242 offset:19456
	s_add_i32 m0, s21, 0xc000
	ds_read_b128 v[194:197], v240
	ds_read_b128 v[198:201], v240 offset:1024
	ds_read_b128 v[202:205], v240 offset:2048
	ds_read_b128 v[206:209], v240 offset:3072
	ds_read_b128 v[210:213], v240 offset:4096
	ds_read_b128 v[214:217], v240 offset:5120
	ds_read_b128 v[218:221], v240 offset:6144
	ds_read_b128 v[222:225], v240 offset:7168
	global_load_lds_dwordx4 v154, s[0:1]
	s_add_i32 m0, s21, 0xe000
	s_nop 0
	global_load_lds_dwordx4 v156, s[0:1]
	s_waitcnt vmcnt(24)
	s_waitcnt lgkmcnt(0)
	s_barrier
	s_setprio 1
	s_waitcnt lgkmcnt(0)
	v_mfma_f32_16x16x32_f16 v[124:127], v[130:133], v[194:197], 0
	v_mfma_f32_16x16x32_f16 v[120:123], v[138:141], v[194:197], 0
	v_mfma_f32_16x16x32_f16 v[116:119], v[130:133], v[202:205], 0
	v_mfma_f32_16x16x32_f16 v[112:115], v[138:141], v[202:205], 0
	v_mfma_f32_16x16x32_f16 v[108:111], v[130:133], v[210:213], 0
	v_mfma_f32_16x16x32_f16 v[104:107], v[138:141], v[210:213], 0
	v_mfma_f32_16x16x32_f16 v[100:103], v[130:133], v[218:221], 0
	v_mfma_f32_16x16x32_f16 v[96:99], v[138:141], v[218:221], 0
	v_mfma_f32_16x16x32_f16 v[124:127], v[134:137], v[198:201], v[124:127]
	v_mfma_f32_16x16x32_f16 v[120:123], v[162:165], v[198:201], v[120:123]
	v_mfma_f32_16x16x32_f16 v[116:119], v[134:137], v[206:209], v[116:119]
	v_mfma_f32_16x16x32_f16 v[112:115], v[162:165], v[206:209], v[112:115]
	v_mfma_f32_16x16x32_f16 v[108:111], v[134:137], v[214:217], v[108:111]
	v_mfma_f32_16x16x32_f16 v[104:107], v[162:165], v[214:217], v[104:107]
	v_mfma_f32_16x16x32_f16 v[100:103], v[134:137], v[222:225], v[100:103]
	v_mfma_f32_16x16x32_f16 v[96:99], v[162:165], v[222:225], v[96:99]
	v_mfma_f32_16x16x32_f16 v[60:63], v[166:169], v[194:197], 0
	v_mfma_f32_16x16x32_f16 v[56:59], v[186:189], v[194:197], 0
	v_mfma_f32_16x16x32_f16 v[52:55], v[166:169], v[202:205], 0
	v_mfma_f32_16x16x32_f16 v[48:51], v[186:189], v[202:205], 0
	v_mfma_f32_16x16x32_f16 v[44:47], v[166:169], v[210:213], 0
	v_mfma_f32_16x16x32_f16 v[40:43], v[186:189], v[210:213], 0
	v_mfma_f32_16x16x32_f16 v[36:39], v[166:169], v[218:221], 0
	v_mfma_f32_16x16x32_f16 v[32:35], v[186:189], v[218:221], 0
	v_mfma_f32_16x16x32_f16 v[60:63], v[170:173], v[198:201], v[60:63]
	v_mfma_f32_16x16x32_f16 v[56:59], v[190:193], v[198:201], v[56:59]
	v_mfma_f32_16x16x32_f16 v[52:55], v[170:173], v[206:209], v[52:55]
	v_mfma_f32_16x16x32_f16 v[48:51], v[190:193], v[206:209], v[48:51]
	v_mfma_f32_16x16x32_f16 v[44:47], v[170:173], v[214:217], v[44:47]
	v_mfma_f32_16x16x32_f16 v[40:43], v[190:193], v[214:217], v[40:43]
	v_mfma_f32_16x16x32_f16 v[36:39], v[170:173], v[222:225], v[36:39]
	v_mfma_f32_16x16x32_f16 v[32:35], v[190:193], v[222:225], v[32:35]
	s_setprio 0
	s_barrier
	s_add_u32 s98, s42, s16
	s_addc_u32 s99, s43, s17
	s_add_u32 s100, s54, s16
	s_addc_u32 s101, s55, s17
	s_add_i32 s68, s68, s20
	s_mov_b32 m0, s68
	ds_read_b128 v[194:197], v240 offset:16384
	ds_read_b128 v[198:201], v240 offset:17408
	ds_read_b128 v[202:205], v240 offset:18432
	ds_read_b128 v[206:209], v240 offset:19456
	ds_read_b128 v[210:213], v240 offset:20480
	ds_read_b128 v[214:217], v240 offset:21504
	ds_read_b128 v[218:221], v240 offset:22528
	ds_read_b128 v[222:225], v240 offset:23552
	global_load_lds_dwordx4 v146, s[42:43]
	s_add_i32 m0, s68, 0x2000
	s_add_u32 s68, s42, 0x40000
	s_addc_u32 s69, s43, 0
	s_add_i32 s70, s70, s20
	global_load_lds_dwordx4 v142, s[42:43]
	s_mov_b32 m0, s70
	s_nop 0
	global_load_lds_dwordx4 v146, s[68:69]
	s_add_i32 m0, s70, 0x2000
	s_nop 0
	global_load_lds_dwordx4 v142, s[68:69]
	s_mov_b32 m0, s21
	s_nop 0
	global_load_lds_dwordx4 v148, s[54:55]
	s_mov_b32 m0, s14
	s_nop 0
	global_load_lds_dwordx4 v144, s[54:55]
	s_waitcnt vmcnt(24)
	s_waitcnt lgkmcnt(0)
	s_barrier
; #define PG8_STAGE(bufoff, gbase, voff) do { _Pragma("unroll") for (int _i = 0; _i < 2; ++_i) \
;         __builtin_amdgcn_global_load_lds((const unsigned*)((const char*)(gbase) + (voff)[_i]), (PG8_LAS unsigned*)(lds + (bufoff) + ldsw + _i * 8192), 16, 0, 0); } while (0)
; #define PG8_LDA(dst, b, h) do { _Pragma("unroll") for (int m = 0; m < 4; ++m) _Pragma("unroll") for (int k = 0; k < 2; ++k) dst[m][k] = *(const PG8_LAS bf16x8*)(lds + PG8_SA(b, h) + aoff + m * 2048 + k * 1024); } while (0)
; #define PG8_LDB(dst, b, h) do { _Pragma("unroll") for (int n = 0; n < 2; ++n) _Pragma("unroll") for (int k = 0; k < 2; ++k) dst[n][k] = *(const PG8_LAS bf16x8*)(lds + PG8_SB(b, h) + boff + n * 2048 + k * 1024); } while (0)
; #define PG8_MMA(ai, bj, At, Bt) do { __builtin_amdgcn_s_setprio(1); _Pragma("unroll") for (int m = 0; m < 4; ++m) _Pragma("unroll") for (int n = 0; n < 2; ++n) _Pragma("unroll") for (int k = 0; k < 2; ++k) \
;         acc[ai][bj][m][n] = mma16<F16>(Bt[n][k], At[m][k], acc[ai][bj][m][n]); __builtin_amdgcn_s_setprio(0); } while (0)
; #define PG8_WAIT_V(n) asm volatile("s_waitcnt vmcnt(" #n ")" ::: "memory")
; #define PG8_WAIT_L(n) asm volatile("s_waitcnt lgkmcnt(" #n ")" ::: "memory")
; #define PG8_BAR __builtin_amdgcn_s_barrier()
; #define PG8_SCHED __builtin_amdgcn_sched_barrier(0)
; template <class Epi, class Sched, bool ALIGN_EPI = false, bool SP2 = false, bool F16 = false>
; __device__ __forceinline__ void gemm_phase(PG8_LAS unsigned char* lds, const Gemm g, const Sched& S, const Epi& E) {
;     ...
;             PG8_WAIT_V(8); PG8_WAIT_L(0); PG8_BAR; PG8_MMA(1, 0, At, B0); PG8_MMA(1, 1, At, B1); PG8_BAR; PG8_SCHED;
;             PG8_LDB(B0, 1, 0); PG8_LDB(B1, 1, 1); PG8_SCHED; PG8_LDA(At, 1, 0); PG8_STAGE(PG8_SA(0, 1), a2 + hstep, voffA);
;             PG8_WAIT_V(8); PG8_WAIT_L(0); PG8_BAR; PG8_MMA(0, 0, At, B0); PG8_MMA(0, 1, At, B1); PG8_BAR; PG8_SCHED;
;             PG8_LDA(At, 1, 1); PG8_STAGE(PG8_SB(1, 0), b3, voffB); PG8_STAGE(PG8_SB(1, 1), b3 + hstep, voffB); PG8_STAGE(PG8_SA(1, 0), a3, voffA);
	s_setprio 1
	s_waitcnt lgkmcnt(0)
	v_mfma_f32_16x16x32_f16 v[92:95], v[130:133], v[194:197], 0
	v_mfma_f32_16x16x32_f16 v[88:91], v[138:141], v[194:197], 0
	v_mfma_f32_16x16x32_f16 v[84:87], v[130:133], v[202:205], 0
	v_mfma_f32_16x16x32_f16 v[80:83], v[138:141], v[202:205], 0
	v_mfma_f32_16x16x32_f16 v[76:79], v[130:133], v[210:213], 0
	v_mfma_f32_16x16x32_f16 v[72:75], v[138:141], v[210:213], 0
	v_mfma_f32_16x16x32_f16 v[68:71], v[130:133], v[218:221], 0
	v_mfma_f32_16x16x32_f16 v[64:67], v[138:141], v[218:221], 0
	v_mfma_f32_16x16x32_f16 v[92:95], v[134:137], v[198:201], v[92:95]
	v_mfma_f32_16x16x32_f16 v[88:91], v[162:165], v[198:201], v[88:91]
	v_mfma_f32_16x16x32_f16 v[84:87], v[134:137], v[206:209], v[84:87]
	v_mfma_f32_16x16x32_f16 v[80:83], v[162:165], v[206:209], v[80:83]
	v_mfma_f32_16x16x32_f16 v[76:79], v[134:137], v[214:217], v[76:79]
	v_mfma_f32_16x16x32_f16 v[72:75], v[162:165], v[214:217], v[72:75]
	v_mfma_f32_16x16x32_f16 v[68:71], v[134:137], v[222:225], v[68:71]
	v_mfma_f32_16x16x32_f16 v[64:67], v[162:165], v[222:225], v[64:67]
	v_mfma_f32_16x16x32_f16 v[28:31], v[166:169], v[194:197], 0
	v_mfma_f32_16x16x32_f16 v[24:27], v[186:189], v[194:197], 0
	v_mfma_f32_16x16x32_f16 v[20:23], v[166:169], v[202:205], 0
	v_mfma_f32_16x16x32_f16 v[16:19], v[186:189], v[202:205], 0
	v_mfma_f32_16x16x32_f16 v[12:15], v[166:169], v[210:213], 0
	v_mfma_f32_16x16x32_f16 v[8:11], v[186:189], v[210:213], 0
	v_mfma_f32_16x16x32_f16 v[4:7], v[166:169], v[218:221], 0
	v_mfma_f32_16x16x32_f16 v[0:3], v[186:189], v[218:221], 0
	v_mfma_f32_16x16x32_f16 v[28:31], v[170:173], v[198:201], v[28:31]
	v_mfma_f32_16x16x32_f16 v[24:27], v[190:193], v[198:201], v[24:27]
	v_mfma_f32_16x16x32_f16 v[20:23], v[170:173], v[206:209], v[20:23]
	v_mfma_f32_16x16x32_f16 v[16:19], v[190:193], v[206:209], v[16:19]
	v_mfma_f32_16x16x32_f16 v[12:15], v[170:173], v[214:217], v[12:15]
	v_mfma_f32_16x16x32_f16 v[8:11], v[190:193], v[214:217], v[8:11]
	v_mfma_f32_16x16x32_f16 v[4:7], v[170:173], v[222:225], v[4:7]
	v_mfma_f32_16x16x32_f16 v[0:3], v[190:193], v[222:225], v[0:3]
	s_setprio 0
	s_barrier
	s_add_i32 s68, 0, 0x18000
	s_add_i32 s69, 0, 0x1c000
	ds_read_b128 v[130:133], v242 offset:32768
	ds_read_b128 v[134:137], v242 offset:33792
	ds_read_b128 v[138:141], v242 offset:34816
	ds_read_b128 v[162:165], v242 offset:35840
	ds_read_b128 v[166:169], v242 offset:49152
	ds_read_b128 v[170:173], v242 offset:50176
	ds_read_b128 v[186:189], v242 offset:51200
	ds_read_b128 v[190:193], v242 offset:52224
	s_add_u32 s54, s54, 0x40000
	s_addc_u32 s55, s55, 0
	s_mov_b32 m0, s15
	ds_read_b128 v[194:197], v240 offset:32768
	ds_read_b128 v[198:201], v240 offset:33792
	ds_read_b128 v[202:205], v240 offset:34816
	ds_read_b128 v[206:209], v240 offset:35840
	ds_read_b128 v[210:213], v240 offset:36864
	ds_read_b128 v[214:217], v240 offset:37888
	ds_read_b128 v[218:221], v240 offset:38912
	ds_read_b128 v[222:225], v240 offset:39936
	global_load_lds_dwordx4 v148, s[54:55]
	s_mov_b32 m0, s37
	s_nop 0
	global_load_lds_dwordx4 v144, s[54:55]
	s_waitcnt vmcnt(8)
	s_waitcnt lgkmcnt(0)
	s_barrier
	s_setprio 1
	s_waitcnt lgkmcnt(0)
	v_mfma_f32_16x16x32_f16 v[124:127], v[130:133], v[194:197], v[124:127]
	v_mfma_f32_16x16x32_f16 v[120:123], v[138:141], v[194:197], v[120:123]
	v_mfma_f32_16x16x32_f16 v[116:119], v[130:133], v[202:205], v[116:119]
	v_mfma_f32_16x16x32_f16 v[112:115], v[138:141], v[202:205], v[112:115]
	v_mfma_f32_16x16x32_f16 v[108:111], v[130:133], v[210:213], v[108:111]
	v_mfma_f32_16x16x32_f16 v[104:107], v[138:141], v[210:213], v[104:107]
	v_mfma_f32_16x16x32_f16 v[100:103], v[130:133], v[218:221], v[100:103]
	v_mfma_f32_16x16x32_f16 v[96:99], v[138:141], v[218:221], v[96:99]
	v_mfma_f32_16x16x32_f16 v[124:127], v[134:137], v[198:201], v[124:127]
	v_mfma_f32_16x16x32_f16 v[120:123], v[162:165], v[198:201], v[120:123]
	v_mfma_f32_16x16x32_f16 v[116:119], v[134:137], v[206:209], v[116:119]
	v_mfma_f32_16x16x32_f16 v[112:115], v[162:165], v[206:209], v[112:115]
	v_mfma_f32_16x16x32_f16 v[108:111], v[134:137], v[214:217], v[108:111]
	v_mfma_f32_16x16x32_f16 v[104:107], v[162:165], v[214:217], v[104:107]
	v_mfma_f32_16x16x32_f16 v[100:103], v[134:137], v[222:225], v[100:103]
	v_mfma_f32_16x16x32_f16 v[96:99], v[162:165], v[222:225], v[96:99]
	v_mfma_f32_16x16x32_f16 v[60:63], v[166:169], v[194:197], v[60:63]
	v_mfma_f32_16x16x32_f16 v[56:59], v[186:189], v[194:197], v[56:59]
	v_mfma_f32_16x16x32_f16 v[52:55], v[166:169], v[202:205], v[52:55]
	v_mfma_f32_16x16x32_f16 v[48:51], v[186:189], v[202:205], v[48:51]
	v_mfma_f32_16x16x32_f16 v[44:47], v[166:169], v[210:213], v[44:47]
	v_mfma_f32_16x16x32_f16 v[40:43], v[186:189], v[210:213], v[40:43]
	v_mfma_f32_16x16x32_f16 v[36:39], v[166:169], v[218:221], v[36:39]
	v_mfma_f32_16x16x32_f16 v[32:35], v[186:189], v[218:221], v[32:35]
	v_mfma_f32_16x16x32_f16 v[60:63], v[170:173], v[198:201], v[60:63]
	v_mfma_f32_16x16x32_f16 v[56:59], v[190:193], v[198:201], v[56:59]
	v_mfma_f32_16x16x32_f16 v[52:55], v[170:173], v[206:209], v[52:55]
	v_mfma_f32_16x16x32_f16 v[48:51], v[190:193], v[206:209], v[48:51]
	v_mfma_f32_16x16x32_f16 v[44:47], v[170:173], v[214:217], v[44:47]
	v_mfma_f32_16x16x32_f16 v[40:43], v[190:193], v[214:217], v[40:43]
	v_mfma_f32_16x16x32_f16 v[36:39], v[170:173], v[222:225], v[36:39]
	v_mfma_f32_16x16x32_f16 v[32:35], v[190:193], v[222:225], v[32:35]
	s_setprio 0
	s_barrier
; #define PG8_STAGE(bufoff, gbase, voff) do { _Pragma("unroll") for (int _i = 0; _i < 2; ++_i) \
;         __builtin_amdgcn_global_load_lds((const unsigned*)((const char*)(gbase) + (voff)[_i]), (PG8_LAS unsigned*)(lds + (bufoff) + ldsw + _i * 8192), 16, 0, 0); } while (0)
; #define PG8_LDA(dst, b, h) do { _Pragma("unroll") for (int m = 0; m < 4; ++m) _Pragma("unroll") for (int k = 0; k < 2; ++k) dst[m][k] = *(const PG8_LAS bf16x8*)(lds + PG8_SA(b, h) + aoff + m * 2048 + k * 1024); } while (0)
; #define PG8_MMA(ai, bj, At, Bt) do { __builtin_amdgcn_s_setprio(1); _Pragma("unroll") for (int m = 0; m < 4; ++m) _Pragma("unroll") for (int n = 0; n < 2; ++n) _Pragma("unroll") for (int k = 0; k < 2; ++k) \
;         acc[ai][bj][m][n] = mma16<F16>(Bt[n][k], At[m][k], acc[ai][bj][m][n]); __builtin_amdgcn_s_setprio(0); } while (0)
; #define PG8_WAIT_V(n) asm volatile("s_waitcnt vmcnt(" #n ")" ::: "memory")
; #define PG8_WAIT_L(n) asm volatile("s_waitcnt lgkmcnt(" #n ")" ::: "memory")
; #define PG8_BAR __builtin_amdgcn_s_barrier()
; #define PG8_SCHED __builtin_amdgcn_sched_barrier(0)
; template <class Epi, class Sched, bool ALIGN_EPI = false, bool SP2 = false, bool F16 = false>
; __device__ __forceinline__ void gemm_phase(PG8_LAS unsigned char* lds, const Gemm g, const Sched& S, const Epi& E) {
;     ...
;             PG8_LDA(At, 1, 1); PG8_STAGE(PG8_SB(1, 0), b3, voffB); PG8_STAGE(PG8_SB(1, 1), b3 + hstep, voffB); PG8_STAGE(PG8_SA(1, 0), a3, voffA);
;             PG8_WAIT_V(8); PG8_WAIT_L(0); PG8_BAR; PG8_MMA(1, 0, At, B0); PG8_MMA(1, 1, At, B1); PG8_BAR; PG8_SCHED;
	s_add_i32 s54, s68, s20
	s_mov_b32 m0, s54
	ds_read_b128 v[194:197], v240 offset:49152
	ds_read_b128 v[198:201], v240 offset:50176
	ds_read_b128 v[202:205], v240 offset:51200
	ds_read_b128 v[206:209], v240 offset:52224
	ds_read_b128 v[210:213], v240 offset:53248
	ds_read_b128 v[214:217], v240 offset:54272
	ds_read_b128 v[218:221], v240 offset:55296
	ds_read_b128 v[222:225], v240 offset:56320
	global_load_lds_dwordx4 v146, s[98:99]
	s_add_i32 m0, s54, 0x2000
	s_add_u32 s42, s42, 0x40080
	s_addc_u32 s43, s43, 0
	s_add_i32 s54, s69, s20
	global_load_lds_dwordx4 v142, s[98:99]
	s_mov_b32 m0, s54
	s_nop 0
	global_load_lds_dwordx4 v146, s[42:43]
	s_add_i32 m0, s54, 0x2000
	s_nop 0
	global_load_lds_dwordx4 v142, s[42:43]
	s_mov_b32 m0, s44
	s_nop 0
	global_load_lds_dwordx4 v148, s[100:101]
	s_mov_b32 m0, s45
	s_nop 0
	global_load_lds_dwordx4 v144, s[100:101]
	s_waitcnt vmcnt(8)
	s_waitcnt lgkmcnt(0)
	s_barrier
	s_setprio 1
	s_waitcnt lgkmcnt(0)
	v_mfma_f32_16x16x32_f16 v[92:95], v[130:133], v[194:197], v[92:95]
	v_mfma_f32_16x16x32_f16 v[88:91], v[138:141], v[194:197], v[88:91]
	v_mfma_f32_16x16x32_f16 v[84:87], v[130:133], v[202:205], v[84:87]
	v_mfma_f32_16x16x32_f16 v[80:83], v[138:141], v[202:205], v[80:83]
	v_mfma_f32_16x16x32_f16 v[76:79], v[130:133], v[210:213], v[76:79]
	v_mfma_f32_16x16x32_f16 v[72:75], v[138:141], v[210:213], v[72:75]
	v_mfma_f32_16x16x32_f16 v[68:71], v[130:133], v[218:221], v[68:71]
	v_mfma_f32_16x16x32_f16 v[64:67], v[138:141], v[218:221], v[64:67]
	v_mfma_f32_16x16x32_f16 v[92:95], v[134:137], v[198:201], v[92:95]
	v_mfma_f32_16x16x32_f16 v[88:91], v[162:165], v[198:201], v[88:91]
	v_mfma_f32_16x16x32_f16 v[84:87], v[134:137], v[206:209], v[84:87]
	v_mfma_f32_16x16x32_f16 v[80:83], v[162:165], v[206:209], v[80:83]
	v_mfma_f32_16x16x32_f16 v[76:79], v[134:137], v[214:217], v[76:79]
	v_mfma_f32_16x16x32_f16 v[72:75], v[162:165], v[214:217], v[72:75]
	v_mfma_f32_16x16x32_f16 v[68:71], v[134:137], v[222:225], v[68:71]
	v_mfma_f32_16x16x32_f16 v[64:67], v[162:165], v[222:225], v[64:67]
	v_mfma_f32_16x16x32_f16 v[28:31], v[166:169], v[194:197], v[28:31]
	v_mfma_f32_16x16x32_f16 v[24:27], v[186:189], v[194:197], v[24:27]
	v_mfma_f32_16x16x32_f16 v[20:23], v[166:169], v[202:205], v[20:23]
	v_mfma_f32_16x16x32_f16 v[16:19], v[186:189], v[202:205], v[16:19]
	v_mfma_f32_16x16x32_f16 v[12:15], v[166:169], v[210:213], v[12:15]
	v_mfma_f32_16x16x32_f16 v[8:11], v[186:189], v[210:213], v[8:11]
	v_mfma_f32_16x16x32_f16 v[4:7], v[166:169], v[218:221], v[4:7]
	v_mfma_f32_16x16x32_f16 v[0:3], v[186:189], v[218:221], v[0:3]
	v_mfma_f32_16x16x32_f16 v[28:31], v[170:173], v[198:201], v[28:31]
	v_mfma_f32_16x16x32_f16 v[24:27], v[190:193], v[198:201], v[24:27]
	v_mfma_f32_16x16x32_f16 v[20:23], v[170:173], v[206:209], v[20:23]
	v_mfma_f32_16x16x32_f16 v[16:19], v[190:193], v[206:209], v[16:19]
	v_mfma_f32_16x16x32_f16 v[12:15], v[170:173], v[214:217], v[12:15]
	v_mfma_f32_16x16x32_f16 v[8:11], v[190:193], v[214:217], v[8:11]
	v_mfma_f32_16x16x32_f16 v[4:7], v[170:173], v[222:225], v[4:7]
	v_mfma_f32_16x16x32_f16 v[0:3], v[190:193], v[222:225], v[0:3]
	s_setprio 0
	s_barrier
	s_add_i32 s67, s67, 2
	s_add_u32 s0, s0, 0x100
	s_addc_u32 s1, s1, 0
	s_add_u32 s59, s59, 0x100
	s_addc_u32 s61, s61, 0
	s_cmp_gt_u32 s67, 13

; #define PG8_STAGE(bufoff, gbase, voff) do { _Pragma("unroll") for (int _i = 0; _i < 2; ++_i) \
;         __builtin_amdgcn_global_load_lds((const unsigned*)((const char*)(gbase) + (voff)[_i]), (PG8_LAS unsigned*)(lds + (bufoff) + ldsw + _i * 8192), 16, 0, 0); } while (0)
; #define PG8_WAIT_V(n) asm volatile("s_waitcnt vmcnt(" #n ")" ::: "memory")
; #define PG8_BAR __builtin_amdgcn_s_barrier()
; template <class Epi, class Sched, bool ALIGN_EPI = false, bool SP2 = false, bool F16 = false>
; __device__ __forceinline__ void gemm_phase(PG8_LAS unsigned char* lds, const Gemm g, const Sched& S, const Epi& E) {
;     ...
;     for (int i = 0; i < 2; ++i) { int R, C; stage_rc(tid * 16 + i * 8192, R, C); const int Rb = Epi::PERM ? ((R & ~31) + perm32(R & 31)) : R;
;         voffA[i] = (unsigned)(R * K + C) * 2u; voffB[i] = (unsigned)(Rb * K + C) * 2u; }
;     const size_t kstep = (size_t)(BK * 2);
;     const size_t hstep = (size_t)HALF * K * 2;
;     const size_t tstep = 2 * hstep;
;     const unsigned ldsw = (unsigned)wid * 1024u;
;     const int aoff = lds_byte(wr * 64 + fr, fq * 8), boff = lds_byte(wc * 32 + fr, fq * 8);
;     ...
;         PG8_STAGE(PG8_SB(0, 0), cB, voffB); PG8_STAGE(PG8_SB(0, 1), cB + hstep, voffB); PG8_STAGE(PG8_SA(0, 0), cA, voffA); PG8_STAGE(PG8_SA(0, 1), cA + hstep, voffA);
;         if (wr == 1) PG8_BAR;
;         PG8_WAIT_V(2); PG8_BAR;
;         PG8_STAGE(PG8_SB(1, 0), cB + kstep, voffB); PG8_STAGE(PG8_SA(1, 0), cA + kstep, voffA); PG8_STAGE(PG8_SB(1, 1), cB + hstep + kstep, voffB);
;         PG8_WAIT_V(6); PG8_BAR;
.LBB0_983:
	s_add_u32 s15, s66, 0x5000
	v_readlane_b32 s12, v255, 14
	s_addc_u32 s20, s67, 0
	v_readlane_b32 s13, v255, 15
	s_lshl_b32 s34, s12, 16
	s_lshl_b64 s[12:13], s[34:35], 2
	v_readlane_b32 s29, v252, 48
	s_add_u32 s12, s29, s12
	s_addc_u32 s13, s28, s13
	v_bfe_u32 v222, v12, 4, 2
	s_add_u32 s12, s12, 0x40000
	v_and_b32_e32 v13, 15, v12
	v_lshlrev_b32_e32 v18, 4, v222
	v_lshlrev_b32_e32 v12, 2, v12
	v_readlane_b32 s48, v254, 56
	s_addc_u32 s13, s13, 0
	v_lshl_or_b32 v223, s21, 6, v13
	v_lshl_or_b32 v13, v13, 6, v18
	s_lshl_b32 s21, s21, 13
	v_and_b32_e32 v12, 32, v12
	s_lshl_b32 s5, s5, 5
	v_mov_b32_e32 v167, v129
	v_readlane_b32 s49, v254, 57
	v_bitop3_b32 v18, v13, s21, v12 bitop3:0xde
	s_and_b32 s21, s5, 0x60
	s_add_i32 m0, s9, 0x18000
	v_lshl_add_u64 v[0:1], v[0:1], 0, s[16:17]
	v_lshl_add_u64 v[14:15], s[48:49], 0, v[166:167]
	v_mov_b32_e32 v165, v129
	s_lshl_b32 s5, s21, 7
	s_waitcnt vmcnt(2)
	s_barrier
	global_load_lds_dwordx4 v[0:1], off
	v_lshl_add_u64 v[0:1], v[2:3], 0, s[16:17]
	s_add_i32 m0, s9, 0x1a000
	s_add_i32 s29, s9, 0x8000
	s_add_i32 s30, s9, 0xa000
	v_lshl_add_u64 v[16:17], s[48:49], 0, v[164:165]
	global_load_lds_dwordx4 v[0:1], off
	v_lshl_add_u64 v[0:1], v[14:15], 0, s[16:17]
	s_mov_b32 m0, s29
	s_add_u32 s38, s50, 0xb0080
	global_load_lds_dwordx4 v[0:1], off
	v_lshl_add_u64 v[0:1], v[16:17], 0, s[16:17]
	s_mov_b32 m0, s30
	s_addc_u32 s39, s51, 0
	global_load_lds_dwordx4 v[0:1], off
	s_add_i32 m0, s9, 0x1c000
	v_lshl_add_u64 v[0:1], s[38:39], 0, v[128:129]
	global_load_lds_dwordx4 v[0:1], off
	v_lshl_add_u64 v[0:1], s[38:39], 0, v[162:163]
	s_add_i32 m0, s9, 0x1e000
	s_movk_i32 s34, 0xb00
	global_load_lds_dwordx4 v[0:1], off
	v_lshrrev_b32_e32 v1, 1, v9
	v_mul_lo_u32 v0, v8, s34
	s_mov_b32 s37, 0xb000
	v_bitop3_b32 v224, v13, s5, v12 bitop3:0xde
	s_cmpk_lt_u32 s4, 0x100
	v_mad_u64_u32 v[0:1], s[4:5], v1, s37, v[0:1]
	v_or_b32_e32 v0, v0, v10
	v_add_lshl_u32 v0, v0, v11, 1
	v_mov_b32_e32 v1, v129
	s_mov_b64 s[40:41], 0xb0080
	v_lshl_add_u64 v[168:169], v[0:1], 0, s[40:41]
	v_lshrrev_b32_e32 v1, 1, v4
	v_mul_lo_u32 v0, v5, s34
	v_mad_u64_u32 v[0:1], s[4:5], v1, s37, v[0:1]
	s_waitcnt vmcnt(6)
	v_or_b32_e32 v0, v0, v6
	v_add_lshl_u32 v0, v0, v7, 1
	v_mov_b32_e32 v1, v129
	v_readlane_b32 s4, v254, 54
	s_cselect_b64 s[44:45], -1, 0
	s_mov_b32 s31, 0
	v_cmp_eq_u32_e64 s[38:39], 0, v222
	v_lshl_add_u64 v[170:171], v[0:1], 0, s[40:41]
	v_add_u32_e32 v225, 0, v18
	v_readlane_b32 s56, v254, 28
	s_mov_b32 s57, s4
	s_waitcnt vmcnt(0)
	s_barrier
	v_readlane_b32 s5, v254, 55
	s_branch .LBB0_986

; #define PG8_STAGE(bufoff, gbase, voff) do { _Pragma("unroll") for (int _i = 0; _i < 2; ++_i) \
;         __builtin_amdgcn_global_load_lds((const unsigned*)((const char*)(gbase) + (voff)[_i]), (PG8_LAS unsigned*)(lds + (bufoff) + ldsw + _i * 8192), 16, 0, 0); } while (0)
; #define PG8_LDA(dst, b, h) do { _Pragma("unroll") for (int m = 0; m < 4; ++m) _Pragma("unroll") for (int k = 0; k < 2; ++k) dst[m][k] = *(const PG8_LAS bf16x8*)(lds + PG8_SA(b, h) + aoff + m * 2048 + k * 1024); } while (0)
; #define PG8_LDB(dst, b, h) do { _Pragma("unroll") for (int n = 0; n < 2; ++n) _Pragma("unroll") for (int k = 0; k < 2; ++k) dst[n][k] = *(const PG8_LAS bf16x8*)(lds + PG8_SB(b, h) + boff + n * 2048 + k * 1024); } while (0)
; #define PG8_MMA(ai, bj, At, Bt) do { __builtin_amdgcn_s_setprio(1); _Pragma("unroll") for (int m = 0; m < 4; ++m) _Pragma("unroll") for (int n = 0; n < 2; ++n) _Pragma("unroll") for (int k = 0; k < 2; ++k) \
;         acc[ai][bj][m][n] = mma16<F16>(Bt[n][k], At[m][k], acc[ai][bj][m][n]); __builtin_amdgcn_s_setprio(0); } while (0)
; #define PG8_WAIT_V(n) asm volatile("s_waitcnt vmcnt(" #n ")" ::: "memory")
; #define PG8_WAIT_L(n) asm volatile("s_waitcnt lgkmcnt(" #n ")" ::: "memory")
; #define PG8_BAR __builtin_amdgcn_s_barrier()
; #define PG8_SCHED __builtin_amdgcn_sched_barrier(0)
; template <class Epi, class Sched, bool ALIGN_EPI = false, bool SP2 = false, bool F16 = false>
; __device__ __forceinline__ void gemm_phase(PG8_LAS unsigned char* lds, const Gemm g, const Sched& S, const Epi& E) {
;     ...
;             PG8_LDB(B0, 0, 0); PG8_LDB(B1, 0, 1); PG8_SCHED; PG8_LDA(At, 0, 0); PG8_STAGE(PG8_SA(1, 1), a1 + hstep, voffA);
;             PG8_WAIT_V(8); PG8_WAIT_L(0); PG8_BAR; PG8_MMA(0, 0, At, B0); PG8_MMA(0, 1, At, B1); PG8_BAR; PG8_SCHED;
;             PG8_LDA(At, 0, 1); PG8_STAGE(PG8_SB(0, 0), b2, voffB); PG8_STAGE(PG8_SB(0, 1), b2 + hstep, voffB); PG8_STAGE(PG8_SA(0, 0), a2, voffA);
;             PG8_WAIT_V(8); PG8_WAIT_L(0); PG8_BAR; PG8_MMA(1, 0, At, B0); PG8_MMA(1, 1, At, B1); PG8_BAR; PG8_SCHED;
.LBB0_996:
	s_add_u32 s4, s50, 0x100
	s_addc_u32 s5, s51, 0
	s_mov_b32 s58, -2
	s_waitcnt lgkmcnt(0)
	v_add_u32_e32 v172, 0x10000, v224
	s_add_u32 s50, s48, 0x100
	s_addc_u32 s51, s49, 0
	s_add_i32 s59, 0, 0x10000
	s_cmp_eq_u32 s58, 40
	s_cselect_b32 s55, s43, s51
	s_cselect_b32 s54, s42, s50
	s_cselect_b32 s53, s47, s5
	s_cselect_b32 s52, s46, s4
	s_add_i32 s60, 0, 0x14000
	ds_read_b128 v[130:133], v172
	ds_read_b128 v[134:137], v172 offset:1024
	ds_read_b128 v[138:141], v172 offset:2048
	ds_read_b128 v[142:145], v172 offset:3072
	ds_read_b128 v[146:149], v172 offset:16384
	ds_read_b128 v[150:153], v172 offset:17408
	ds_read_b128 v[154:157], v172 offset:18432
	ds_read_b128 v[158:161], v172 offset:19456
	s_add_i32 m0, s9, 0xc000
	ds_read_b128 v[186:189], v225
	ds_read_b128 v[190:193], v225 offset:1024
	ds_read_b128 v[194:197], v225 offset:2048
	ds_read_b128 v[198:201], v225 offset:3072
	ds_read_b128 v[202:205], v225 offset:4096
	ds_read_b128 v[206:209], v225 offset:5120
	ds_read_b128 v[210:213], v225 offset:6144
	ds_read_b128 v[214:217], v225 offset:7168
	global_load_lds_dwordx4 v168, s[48:49]
	s_add_i32 m0, s9, 0xe000
	s_nop 0
	global_load_lds_dwordx4 v170, s[48:49]
	s_waitcnt vmcnt(24)
	s_waitcnt lgkmcnt(0)
	s_barrier
	s_setprio 1
	s_waitcnt lgkmcnt(0)
	v_mfma_f32_16x16x32_bf16 v[124:127], v[130:133], v[186:189], 0
	v_mfma_f32_16x16x32_bf16 v[120:123], v[138:141], v[186:189], 0
	v_mfma_f32_16x16x32_bf16 v[116:119], v[130:133], v[194:197], 0
	v_mfma_f32_16x16x32_bf16 v[112:115], v[138:141], v[194:197], 0
	v_mfma_f32_16x16x32_bf16 v[108:111], v[130:133], v[202:205], 0
	v_mfma_f32_16x16x32_bf16 v[104:107], v[138:141], v[202:205], 0
	v_mfma_f32_16x16x32_bf16 v[100:103], v[130:133], v[210:213], 0
	v_mfma_f32_16x16x32_bf16 v[96:99], v[138:141], v[210:213], 0
	v_mfma_f32_16x16x32_bf16 v[124:127], v[134:137], v[190:193], v[124:127]
	v_mfma_f32_16x16x32_bf16 v[120:123], v[142:145], v[190:193], v[120:123]
	v_mfma_f32_16x16x32_bf16 v[116:119], v[134:137], v[198:201], v[116:119]
	v_mfma_f32_16x16x32_bf16 v[112:115], v[142:145], v[198:201], v[112:115]
	v_mfma_f32_16x16x32_bf16 v[108:111], v[134:137], v[206:209], v[108:111]
	v_mfma_f32_16x16x32_bf16 v[104:107], v[142:145], v[206:209], v[104:107]
	v_mfma_f32_16x16x32_bf16 v[100:103], v[134:137], v[214:217], v[100:103]
	v_mfma_f32_16x16x32_bf16 v[96:99], v[142:145], v[214:217], v[96:99]
	v_mfma_f32_16x16x32_bf16 v[60:63], v[146:149], v[186:189], 0
	v_mfma_f32_16x16x32_bf16 v[56:59], v[154:157], v[186:189], 0
	v_mfma_f32_16x16x32_bf16 v[52:55], v[146:149], v[194:197], 0
	v_mfma_f32_16x16x32_bf16 v[48:51], v[154:157], v[194:197], 0
	v_mfma_f32_16x16x32_bf16 v[44:47], v[146:149], v[202:205], 0
	v_mfma_f32_16x16x32_bf16 v[40:43], v[154:157], v[202:205], 0
	v_mfma_f32_16x16x32_bf16 v[36:39], v[146:149], v[210:213], 0
	v_mfma_f32_16x16x32_bf16 v[32:35], v[154:157], v[210:213], 0
	v_mfma_f32_16x16x32_bf16 v[60:63], v[150:153], v[190:193], v[60:63]
	v_mfma_f32_16x16x32_bf16 v[56:59], v[158:161], v[190:193], v[56:59]
	v_mfma_f32_16x16x32_bf16 v[52:55], v[150:153], v[198:201], v[52:55]
	v_mfma_f32_16x16x32_bf16 v[48:51], v[158:161], v[198:201], v[48:51]
	v_mfma_f32_16x16x32_bf16 v[44:47], v[150:153], v[206:209], v[44:47]
	v_mfma_f32_16x16x32_bf16 v[40:43], v[158:161], v[206:209], v[40:43]
	v_mfma_f32_16x16x32_bf16 v[36:39], v[150:153], v[214:217], v[36:39]
	v_mfma_f32_16x16x32_bf16 v[32:35], v[158:161], v[214:217], v[32:35]
	s_setprio 0
	s_barrier
	s_add_u32 s98, s52, s16
	s_addc_u32 s99, s53, s17
	s_add_u32 s100, s54, s16
	s_addc_u32 s101, s55, s17
	s_add_i32 s48, s59, s8
	s_mov_b32 m0, s48
	ds_read_b128 v[186:189], v225 offset:16384
	ds_read_b128 v[190:193], v225 offset:17408
	ds_read_b128 v[194:197], v225 offset:18432
	ds_read_b128 v[198:201], v225 offset:19456
	ds_read_b128 v[202:205], v225 offset:20480
	ds_read_b128 v[206:209], v225 offset:21504
	ds_read_b128 v[210:213], v225 offset:22528
	ds_read_b128 v[214:217], v225 offset:23552
	global_load_lds_dwordx4 v128, s[52:53]
	s_add_i32 m0, s48, 0x2000
	s_add_u32 s48, s52, 0xb0000
	s_addc_u32 s49, s53, 0
	s_add_i32 s59, s60, s8
	global_load_lds_dwordx4 v162, s[52:53]
	s_mov_b32 m0, s59
	s_nop 0
	global_load_lds_dwordx4 v128, s[48:49]
	s_add_i32 m0, s59, 0x2000
	s_nop 0
	global_load_lds_dwordx4 v162, s[48:49]
	s_mov_b32 m0, s9
	s_nop 0
	global_load_lds_dwordx4 v166, s[54:55]
	s_mov_b32 m0, s10
	s_nop 0
	global_load_lds_dwordx4 v164, s[54:55]
	s_waitcnt vmcnt(24)
	s_waitcnt lgkmcnt(0)
	s_barrier
	s_setprio 1
	s_waitcnt lgkmcnt(0)
	v_mfma_f32_16x16x32_bf16 v[92:95], v[130:133], v[186:189], 0
	v_mfma_f32_16x16x32_bf16 v[88:91], v[138:141], v[186:189], 0
	v_mfma_f32_16x16x32_bf16 v[84:87], v[130:133], v[194:197], 0
	v_mfma_f32_16x16x32_bf16 v[80:83], v[138:141], v[194:197], 0
	v_mfma_f32_16x16x32_bf16 v[76:79], v[130:133], v[202:205], 0
	v_mfma_f32_16x16x32_bf16 v[72:75], v[138:141], v[202:205], 0
	v_mfma_f32_16x16x32_bf16 v[68:71], v[130:133], v[210:213], 0
	v_mfma_f32_16x16x32_bf16 v[64:67], v[138:141], v[210:213], 0
	v_mfma_f32_16x16x32_bf16 v[92:95], v[134:137], v[190:193], v[92:95]
	v_mfma_f32_16x16x32_bf16 v[88:91], v[142:145], v[190:193], v[88:91]
	v_mfma_f32_16x16x32_bf16 v[84:87], v[134:137], v[198:201], v[84:87]
	v_mfma_f32_16x16x32_bf16 v[80:83], v[142:145], v[198:201], v[80:83]
	v_mfma_f32_16x16x32_bf16 v[76:79], v[134:137], v[206:209], v[76:79]
	v_mfma_f32_16x16x32_bf16 v[72:75], v[142:145], v[206:209], v[72:75]
	v_mfma_f32_16x16x32_bf16 v[68:71], v[134:137], v[214:217], v[68:71]
	v_mfma_f32_16x16x32_bf16 v[64:67], v[142:145], v[214:217], v[64:67]
	v_mfma_f32_16x16x32_bf16 v[28:31], v[146:149], v[186:189], 0
	v_mfma_f32_16x16x32_bf16 v[24:27], v[154:157], v[186:189], 0
	v_mfma_f32_16x16x32_bf16 v[20:23], v[146:149], v[194:197], 0
	v_mfma_f32_16x16x32_bf16 v[16:19], v[154:157], v[194:197], 0
	v_mfma_f32_16x16x32_bf16 v[12:15], v[146:149], v[202:205], 0
	v_mfma_f32_16x16x32_bf16 v[8:11], v[154:157], v[202:205], 0
	v_mfma_f32_16x16x32_bf16 v[4:7], v[146:149], v[210:213], 0
	v_mfma_f32_16x16x32_bf16 v[0:3], v[154:157], v[210:213], 0
	v_mfma_f32_16x16x32_bf16 v[28:31], v[150:153], v[190:193], v[28:31]
	v_mfma_f32_16x16x32_bf16 v[24:27], v[158:161], v[190:193], v[24:27]
	v_mfma_f32_16x16x32_bf16 v[20:23], v[150:153], v[198:201], v[20:23]
	v_mfma_f32_16x16x32_bf16 v[16:19], v[158:161], v[198:201], v[16:19]
	v_mfma_f32_16x16x32_bf16 v[12:15], v[150:153], v[206:209], v[12:15]
	v_mfma_f32_16x16x32_bf16 v[8:11], v[158:161], v[206:209], v[8:11]
	v_mfma_f32_16x16x32_bf16 v[4:7], v[150:153], v[214:217], v[4:7]
	v_mfma_f32_16x16x32_bf16 v[0:3], v[158:161], v[214:217], v[0:3]
	s_setprio 0
	s_barrier
; #define PG8_STAGE(bufoff, gbase, voff) do { _Pragma("unroll") for (int _i = 0; _i < 2; ++_i) \
;         __builtin_amdgcn_global_load_lds((const unsigned*)((const char*)(gbase) + (voff)[_i]), (PG8_LAS unsigned*)(lds + (bufoff) + ldsw + _i * 8192), 16, 0, 0); } while (0)
; #define PG8_LDA(dst, b, h) do { _Pragma("unroll") for (int m = 0; m < 4; ++m) _Pragma("unroll") for (int k = 0; k < 2; ++k) dst[m][k] = *(const PG8_LAS bf16x8*)(lds + PG8_SA(b, h) + aoff + m * 2048 + k * 1024); } while (0)
; #define PG8_LDB(dst, b, h) do { _Pragma("unroll") for (int n = 0; n < 2; ++n) _Pragma("unroll") for (int k = 0; k < 2; ++k) dst[n][k] = *(const PG8_LAS bf16x8*)(lds + PG8_SB(b, h) + boff + n * 2048 + k * 1024); } while (0)
; #define PG8_MMA(ai, bj, At, Bt) do { __builtin_amdgcn_s_setprio(1); _Pragma("unroll") for (int m = 0; m < 4; ++m) _Pragma("unroll") for (int n = 0; n < 2; ++n) _Pragma("unroll") for (int k = 0; k < 2; ++k) \
;         acc[ai][bj][m][n] = mma16<F16>(Bt[n][k], At[m][k], acc[ai][bj][m][n]); __builtin_amdgcn_s_setprio(0); } while (0)
; #define PG8_WAIT_V(n) asm volatile("s_waitcnt vmcnt(" #n ")" ::: "memory")
; #define PG8_WAIT_L(n) asm volatile("s_waitcnt lgkmcnt(" #n ")" ::: "memory")
; #define PG8_BAR __builtin_amdgcn_s_barrier()
; #define PG8_SCHED __builtin_amdgcn_sched_barrier(0)
; template <class Epi, class Sched, bool ALIGN_EPI = false, bool SP2 = false, bool F16 = false>
; __device__ __forceinline__ void gemm_phase(PG8_LAS unsigned char* lds, const Gemm g, const Sched& S, const Epi& E) {
;     ...
;             PG8_LDB(B0, 1, 0); PG8_LDB(B1, 1, 1); PG8_SCHED; PG8_LDA(At, 1, 0); PG8_STAGE(PG8_SA(0, 1), a2 + hstep, voffA);
;             PG8_WAIT_V(8); PG8_WAIT_L(0); PG8_BAR; PG8_MMA(0, 0, At, B0); PG8_MMA(0, 1, At, B1); PG8_BAR; PG8_SCHED;
;             PG8_LDA(At, 1, 1); PG8_STAGE(PG8_SB(1, 0), b3, voffB); PG8_STAGE(PG8_SB(1, 1), b3 + hstep, voffB); PG8_STAGE(PG8_SA(1, 0), a3, voffA);
;             PG8_WAIT_V(8); PG8_WAIT_L(0); PG8_BAR; PG8_MMA(1, 0, At, B0); PG8_MMA(1, 1, At, B1); PG8_BAR; PG8_SCHED;
	s_add_i32 s59, 0, 0x18000
	s_add_i32 s60, 0, 0x1c000
	ds_read_b128 v[130:133], v172 offset:32768
	ds_read_b128 v[134:137], v172 offset:33792
	ds_read_b128 v[138:141], v172 offset:34816
	ds_read_b128 v[142:145], v172 offset:35840
	ds_read_b128 v[146:149], v172 offset:49152
	ds_read_b128 v[150:153], v172 offset:50176
	ds_read_b128 v[154:157], v172 offset:51200
	ds_read_b128 v[158:161], v172 offset:52224
	s_add_u32 s48, s54, 0xb0000
	s_addc_u32 s49, s55, 0
	s_mov_b32 m0, s11
	ds_read_b128 v[186:189], v225 offset:32768
	ds_read_b128 v[190:193], v225 offset:33792
	ds_read_b128 v[194:197], v225 offset:34816
	ds_read_b128 v[198:201], v225 offset:35840
	ds_read_b128 v[202:205], v225 offset:36864
	ds_read_b128 v[206:209], v225 offset:37888
	ds_read_b128 v[210:213], v225 offset:38912
	ds_read_b128 v[214:217], v225 offset:39936
	global_load_lds_dwordx4 v166, s[48:49]
	s_mov_b32 m0, s14
	s_nop 0
	global_load_lds_dwordx4 v164, s[48:49]
	s_waitcnt vmcnt(8)
	s_waitcnt lgkmcnt(0)
	s_barrier
	s_setprio 1
	s_waitcnt lgkmcnt(0)
	v_mfma_f32_16x16x32_bf16 v[124:127], v[130:133], v[186:189], v[124:127]
	v_mfma_f32_16x16x32_bf16 v[120:123], v[138:141], v[186:189], v[120:123]
	v_mfma_f32_16x16x32_bf16 v[116:119], v[130:133], v[194:197], v[116:119]
	v_mfma_f32_16x16x32_bf16 v[112:115], v[138:141], v[194:197], v[112:115]
	v_mfma_f32_16x16x32_bf16 v[108:111], v[130:133], v[202:205], v[108:111]
	v_mfma_f32_16x16x32_bf16 v[104:107], v[138:141], v[202:205], v[104:107]
	v_mfma_f32_16x16x32_bf16 v[100:103], v[130:133], v[210:213], v[100:103]
	v_mfma_f32_16x16x32_bf16 v[96:99], v[138:141], v[210:213], v[96:99]
	v_mfma_f32_16x16x32_bf16 v[124:127], v[134:137], v[190:193], v[124:127]
	v_mfma_f32_16x16x32_bf16 v[120:123], v[142:145], v[190:193], v[120:123]
	v_mfma_f32_16x16x32_bf16 v[116:119], v[134:137], v[198:201], v[116:119]
	v_mfma_f32_16x16x32_bf16 v[112:115], v[142:145], v[198:201], v[112:115]
	v_mfma_f32_16x16x32_bf16 v[108:111], v[134:137], v[206:209], v[108:111]
	v_mfma_f32_16x16x32_bf16 v[104:107], v[142:145], v[206:209], v[104:107]
	v_mfma_f32_16x16x32_bf16 v[100:103], v[134:137], v[214:217], v[100:103]
	v_mfma_f32_16x16x32_bf16 v[96:99], v[142:145], v[214:217], v[96:99]
	v_mfma_f32_16x16x32_bf16 v[60:63], v[146:149], v[186:189], v[60:63]
	v_mfma_f32_16x16x32_bf16 v[56:59], v[154:157], v[186:189], v[56:59]
	v_mfma_f32_16x16x32_bf16 v[52:55], v[146:149], v[194:197], v[52:55]
	v_mfma_f32_16x16x32_bf16 v[48:51], v[154:157], v[194:197], v[48:51]
	v_mfma_f32_16x16x32_bf16 v[44:47], v[146:149], v[202:205], v[44:47]
	v_mfma_f32_16x16x32_bf16 v[40:43], v[154:157], v[202:205], v[40:43]
	v_mfma_f32_16x16x32_bf16 v[36:39], v[146:149], v[210:213], v[36:39]
	v_mfma_f32_16x16x32_bf16 v[32:35], v[154:157], v[210:213], v[32:35]
	v_mfma_f32_16x16x32_bf16 v[60:63], v[150:153], v[190:193], v[60:63]
	v_mfma_f32_16x16x32_bf16 v[56:59], v[158:161], v[190:193], v[56:59]
	v_mfma_f32_16x16x32_bf16 v[52:55], v[150:153], v[198:201], v[52:55]
	v_mfma_f32_16x16x32_bf16 v[48:51], v[158:161], v[198:201], v[48:51]
	v_mfma_f32_16x16x32_bf16 v[44:47], v[150:153], v[206:209], v[44:47]
	v_mfma_f32_16x16x32_bf16 v[40:43], v[158:161], v[206:209], v[40:43]
	v_mfma_f32_16x16x32_bf16 v[36:39], v[150:153], v[214:217], v[36:39]
	v_mfma_f32_16x16x32_bf16 v[32:35], v[158:161], v[214:217], v[32:35]
	s_setprio 0
	s_barrier
	s_add_i32 s48, s59, s8
	s_mov_b32 m0, s48
	ds_read_b128 v[186:189], v225 offset:49152
	ds_read_b128 v[190:193], v225 offset:50176
	ds_read_b128 v[194:197], v225 offset:51200
	ds_read_b128 v[198:201], v225 offset:52224
	ds_read_b128 v[202:205], v225 offset:53248
	ds_read_b128 v[206:209], v225 offset:54272
	ds_read_b128 v[210:213], v225 offset:55296
	ds_read_b128 v[214:217], v225 offset:56320
	global_load_lds_dwordx4 v128, s[98:99]
	s_add_i32 m0, s48, 0x2000
	s_add_u32 s48, s52, 0xb0080
	s_addc_u32 s49, s53, 0
	s_add_i32 s52, s60, s8
	global_load_lds_dwordx4 v162, s[98:99]
	s_mov_b32 m0, s52
	s_nop 0
	global_load_lds_dwordx4 v128, s[48:49]
	s_add_i32 m0, s52, 0x2000
	s_nop 0
	global_load_lds_dwordx4 v162, s[48:49]
	s_mov_b32 m0, s29
	s_nop 0
	global_load_lds_dwordx4 v166, s[100:101]
	s_mov_b32 m0, s30
	s_nop 0
	global_load_lds_dwordx4 v164, s[100:101]
	s_waitcnt vmcnt(8)
	s_waitcnt lgkmcnt(0)
	s_barrier
	s_setprio 1
	s_waitcnt lgkmcnt(0)
	v_mfma_f32_16x16x32_bf16 v[92:95], v[130:133], v[186:189], v[92:95]
	v_mfma_f32_16x16x32_bf16 v[88:91], v[138:141], v[186:189], v[88:91]
	v_mfma_f32_16x16x32_bf16 v[84:87], v[130:133], v[194:197], v[84:87]
	v_mfma_f32_16x16x32_bf16 v[80:83], v[138:141], v[194:197], v[80:83]
	v_mfma_f32_16x16x32_bf16 v[76:79], v[130:133], v[202:205], v[76:79]
	v_mfma_f32_16x16x32_bf16 v[72:75], v[138:141], v[202:205], v[72:75]
	v_mfma_f32_16x16x32_bf16 v[68:71], v[130:133], v[210:213], v[68:71]
	v_mfma_f32_16x16x32_bf16 v[64:67], v[138:141], v[210:213], v[64:67]
	v_mfma_f32_16x16x32_bf16 v[92:95], v[134:137], v[190:193], v[92:95]
	v_mfma_f32_16x16x32_bf16 v[88:91], v[142:145], v[190:193], v[88:91]
	v_mfma_f32_16x16x32_bf16 v[84:87], v[134:137], v[198:201], v[84:87]
	v_mfma_f32_16x16x32_bf16 v[80:83], v[142:145], v[198:201], v[80:83]
	v_mfma_f32_16x16x32_bf16 v[76:79], v[134:137], v[206:209], v[76:79]
	v_mfma_f32_16x16x32_bf16 v[72:75], v[142:145], v[206:209], v[72:75]
	v_mfma_f32_16x16x32_bf16 v[68:71], v[134:137], v[214:217], v[68:71]
	v_mfma_f32_16x16x32_bf16 v[64:67], v[142:145], v[214:217], v[64:67]
	v_mfma_f32_16x16x32_bf16 v[28:31], v[146:149], v[186:189], v[28:31]
	v_mfma_f32_16x16x32_bf16 v[24:27], v[154:157], v[186:189], v[24:27]
	v_mfma_f32_16x16x32_bf16 v[20:23], v[146:149], v[194:197], v[20:23]
	v_mfma_f32_16x16x32_bf16 v[16:19], v[154:157], v[194:197], v[16:19]
	v_mfma_f32_16x16x32_bf16 v[12:15], v[146:149], v[202:205], v[12:15]
	v_mfma_f32_16x16x32_bf16 v[8:11], v[154:157], v[202:205], v[8:11]
	v_mfma_f32_16x16x32_bf16 v[4:7], v[146:149], v[210:213], v[4:7]
	v_mfma_f32_16x16x32_bf16 v[0:3], v[154:157], v[210:213], v[0:3]
	v_mfma_f32_16x16x32_bf16 v[28:31], v[150:153], v[190:193], v[28:31]
	v_mfma_f32_16x16x32_bf16 v[24:27], v[158:161], v[190:193], v[24:27]
	v_mfma_f32_16x16x32_bf16 v[20:23], v[150:153], v[198:201], v[20:23]
	v_mfma_f32_16x16x32_bf16 v[16:19], v[158:161], v[198:201], v[16:19]
	v_mfma_f32_16x16x32_bf16 v[12:15], v[150:153], v[206:209], v[12:15]
	v_mfma_f32_16x16x32_bf16 v[8:11], v[158:161], v[206:209], v[8:11]
	v_mfma_f32_16x16x32_bf16 v[4:7], v[150:153], v[214:217], v[4:7]
	v_mfma_f32_16x16x32_bf16 v[0:3], v[158:161], v[214:217], v[0:3]
	s_setprio 0
	s_barrier
	s_add_i32 s58, s58, 2
	s_add_u32 s4, s4, 0x100
	s_addc_u32 s5, s5, 0
	s_cmp_gt_u32 s58, 41
	s_mov_b64 s[48:49], s[50:51]
